# removed 94 dead kernel-argument reloads (load_ctx re-reads every pointer with a wait at each phase entry)
# baseline (speedup 1.0000x reference)
.LBB0_19:
	s_load_dwordx2 s[6:7], s[0:1], 0
	s_waitcnt lgkmcnt(0)
	s_load_dwordx2 s[12:13], s[0:1], 8
	s_waitcnt lgkmcnt(0)
	s_load_dwordx2 s[14:15], s[0:1], 16
	s_waitcnt lgkmcnt(0)
	s_load_dwordx2 s[16:17], s[0:1], 24
	s_waitcnt lgkmcnt(0)
	v_mov_b32_e32 v1, v184
	s_lshl_b32 s80, s78, 3
	s_movk_i32 s18, 0x4000
	s_lshl_b32 s76, s60, 3
	s_load_dwordx2 s[8:9], s[0:1], 64
	s_waitcnt lgkmcnt(0)
	v_mbcnt_lo_u32_b32 v78, -1, 0
	s_nop 0
	s_nop 0
	s_nop 0
	s_load_dwordx2 s[10:11], s[0:1], 0x68
	s_waitcnt lgkmcnt(0)
	s_nop 0
	v_ashrrev_i32_e32 v2, 6, v1
	v_add_u32_e32 v79, s80, v2
	v_and_b32_e32 v0, 63, v1
	v_cmp_gt_i32_e32 vcc, s18, v79
	s_and_saveexec_b64 s[18:19], vcc
	s_cbranch_execz .LBB0_24
	v_mbcnt_hi_u32_b32 v3, -1, v78
	v_and_b32_e32 v4, 64, v3
	v_add_u32_e32 v4, 64, v4
	v_xor_b32_e32 v5, 1, v3
	v_cmp_lt_i32_e32 vcc, v5, v4
	s_ashr_i32 s81, s80, 31
	s_mov_b64 s[20:21], 0x1400000
	v_cndmask_b32_e32 v5, v3, v5, vcc
	v_lshlrev_b32_e32 v10, 2, v5
	v_xor_b32_e32 v5, 2, v3
	v_cmp_lt_i32_e32 vcc, v5, v4
	s_ashr_i32 s77, s76, 31
	s_mov_b64 s[22:23], 0x2000400
	v_cndmask_b32_e32 v5, v3, v5, vcc
	v_lshlrev_b32_e32 v11, 2, v5
	v_xor_b32_e32 v5, 4, v3
	v_cmp_lt_i32_e32 vcc, v5, v4
	s_lshl_b64 s[24:25], s[76:77], 12
	s_mov_b64 s[26:27], 0
	v_cndmask_b32_e32 v5, v3, v5, vcc
	v_lshlrev_b32_e32 v12, 2, v5
	v_xor_b32_e32 v5, 8, v3
	v_cmp_lt_i32_e32 vcc, v5, v4
	s_movk_i32 s28, 0x3fff
	s_nop 0
	v_cndmask_b32_e32 v5, v3, v5, vcc
	v_lshlrev_b32_e32 v13, 2, v5
	v_xor_b32_e32 v5, 16, v3
	v_cmp_lt_i32_e32 vcc, v5, v4
	s_nop 1
	v_cndmask_b32_e32 v5, v3, v5, vcc
	v_lshlrev_b32_e32 v14, 2, v5
	v_xor_b32_e32 v5, 32, v3
	v_cmp_lt_i32_e32 vcc, v5, v4
	s_nop 1
	v_cndmask_b32_e32 v3, v3, v5, vcc
	v_lshlrev_b32_e32 v15, 2, v3
	v_ashrrev_i32_e32 v3, 31, v2
	v_lshl_add_u64 v[8:9], v[2:3], 0, s[80:81]
	v_lshl_add_u64 v[4:5], v[8:9], 2, s[10:11]
	v_lshlrev_b64 v[6:7], 11, v[8:9]
	v_lshlrev_b64 v[8:9], 12, v[8:9]
	v_lshl_or_b32 v6, v0, 3, v6
	v_lshl_or_b32 v8, v0, 4, v8
	v_lshl_add_u64 v[6:7], s[10:11], 0, v[6:7]
	v_lshl_add_u64 v[8:9], s[6:7], 0, v[8:9]
	s_mov_b64 s[6:7], 0xc00
	v_cmp_eq_u32_e32 vcc, 0, v0
	v_lshl_add_u64 v[4:5], v[4:5], 0, s[20:21]
	s_lshl_b64 s[20:21], s[76:77], 2
	v_lshl_add_u64 v[6:7], v[6:7], 0, s[22:23]
	s_lshl_b64 s[22:23], s[76:77], 11
	v_lshl_add_u64 v[8:9], v[8:9], 0, s[6:7]
	v_mov_b32_e32 v3, v79
	s_branch .LBB0_22

.LBB0_253:
	v_writelane_b32 v252, s2, 20
	v_mov_b32_e32 v8, v184
	s_mov_b32 s17, s81
	v_writelane_b32 v252, s3, 21
	s_lshl_b32 s2, s16, 14
	s_mov_b32 s3, s81
	v_writelane_b32 v252, s2, 22
	s_nop 0
	s_nop 0
	s_load_dwordx2 s[20:21], s[0:1], 0x50
	s_waitcnt lgkmcnt(0)
	v_writelane_b32 v252, s3, 23
	s_lshl_b32 s2, s16, 8
	s_mov_b32 s3, s81
	s_load_dwordx2 s[10:11], s[0:1], 0x60
	s_waitcnt lgkmcnt(0)
	v_writelane_b32 v252, s2, 24
	s_load_dwordx2 s[22:23], s[0:1], 0x68
	s_waitcnt lgkmcnt(0)
	s_nop 0
	v_readfirstlane_b32 s24, v8
	v_writelane_b32 v252, s3, 25
	v_readlane_b32 s2, v253, 6
	v_readlane_b32 s3, v253, 7
	s_andn2_b64 vcc, exec, s[2:3]
	v_writelane_b32 v252, s14, 26
	s_nop 1
	v_writelane_b32 v252, s15, 27
	s_cbranch_vccnz .LBB0_483
	v_lshlrev_b32_e32 v0, 4, v8
	s_waitcnt lgkmcnt(0)
	v_add_u32_e32 v1, 0x2000, v0
	v_ashrrev_i32_e32 v2, 31, v1
	v_lshrrev_b32_e32 v2, 22, v2
	v_add_u32_e32 v2, v1, v2
	v_ashrrev_i32_e32 v9, 10, v2
	v_mul_i32_i24_e32 v2, 0x400, v9
	v_sub_u32_e32 v1, v1, v2
	v_lshrrev_b32_e32 v2, 4, v1
	v_bitop3_b32 v1, v2, v1, 32 bitop3:0x6c
	v_ashrrev_i32_e32 v2, 31, v1
	v_lshrrev_b32_e32 v2, 26, v2
	v_add_u32_e32 v2, v1, v2
	v_lshlrev_b32_e32 v3, 3, v9
	v_ashrrev_i32_e32 v10, 6, v2
	v_and_b32_e32 v3, -16, v3
	v_add_u32_e32 v3, v10, v3
	v_and_b32_e32 v4, 3, v10
	s_mov_b32 s2, 0x1fffe0
	v_lshrrev_b32_e32 v5, 2, v3
	v_lshlrev_b32_e32 v6, 1, v3
	v_and_b32_e32 v2, 0xc0, v2
	v_and_or_b32 v4, v3, s2, v4
	v_and_b32_e32 v5, 4, v5
	v_and_b32_e32 v6, 24, v6
	v_sub_u32_e32 v1, v1, v2
	v_or3_b32 v4, v4, v5, v6
	v_lshlrev_b32_e32 v5, 5, v9
	v_ashrrev_i16_sdwa v1, v193, sext(v1) dst_sel:DWORD dst_unused:UNUSED_PAD src0_sel:DWORD src1_sel:BYTE_0
	v_and_b32_e32 v5, 32, v5
	v_bfe_i32 v11, v1, 0, 16
	v_add_lshl_u32 v1, v5, v11, 1
	v_lshl_add_u32 v136, v4, 11, v1
	v_lshl_add_u32 v138, v3, 11, v1
	v_bfe_i32 v1, v8, 27, 1
	v_lshrrev_b32_e32 v1, 22, v1
	v_add_u32_e32 v1, v0, v1
	v_and_b32_e32 v1, 0xfffffc00, v1
	v_sub_u32_e32 v0, v0, v1
	v_lshrrev_b32_e32 v1, 4, v0
	v_ashrrev_i32_e32 v2, 31, v8
	v_bitop3_b32 v0, v1, v0, 32 bitop3:0x6c
	v_lshrrev_b32_e32 v2, 26, v2
	v_ashrrev_i32_e32 v1, 31, v0
	v_add_u32_e32 v2, v8, v2
	v_lshrrev_b32_e32 v1, 26, v1
	v_ashrrev_i32_e32 v13, 6, v2
	v_add_u32_e32 v1, v0, v1
	v_lshlrev_b32_e32 v2, 3, v13
	s_add_u32 s73, s22, 0x2000000
	v_ashrrev_i32_e32 v12, 6, v1
	v_and_b32_e32 v2, -16, v2
	s_addc_u32 s74, s23, 0
	s_lshl_b64 s[10:11], s[16:17], 23
	v_add_u32_e32 v2, v12, v2
	s_add_u32 s75, s22, s10
	v_and_b32_e32 v3, 3, v12
	v_lshrrev_b32_e32 v4, 2, v2
	v_lshlrev_b32_e32 v5, 1, v2
	v_and_b32_e32 v1, 0xc0, v1
	s_addc_u32 s12, s23, s11
	s_ashr_i32 s25, s24, 6
	v_and_or_b32 v3, v2, s2, v3
	v_and_b32_e32 v4, 4, v4
	v_and_b32_e32 v5, 24, v5
	v_sub_u32_e32 v0, v0, v1
	s_ashr_i32 s18, s24, 8
	s_lshl_b32 s13, s25, 10
	v_or3_b32 v3, v3, v4, v5
	v_lshlrev_b32_e32 v4, 5, v13
	v_ashrrev_i16_sdwa v0, v193, sext(v0) dst_sel:DWORD dst_unused:UNUSED_PAD src0_sel:DWORD src1_sel:BYTE_0
	v_readlane_b32 s2, v253, 58
	v_and_b32_e32 v4, 32, v4
	v_bfe_i32 v14, v0, 0, 16
	v_readlane_b32 s3, v253, 59
	s_add_u32 s34, s75, s2
	v_add_lshl_u32 v0, v4, v14, 1
	s_addc_u32 s35, s12, s3
	s_add_i32 s14, s13, 0
	v_lshl_add_u32 v140, v3, 11, v0
	s_add_i32 m0, s14, 0x10000
	v_readlane_b32 s2, v253, 56
	global_load_lds_dwordx4 v140, s[34:35]
	s_add_i32 m0, s14, 0x12000
	s_add_u32 s10, s34, 0x40000
	global_load_lds_dwordx4 v136, s[34:35]
	s_addc_u32 s11, s35, 0
	s_add_i32 m0, s14, 0x14000
	v_readlane_b32 s3, v253, 57
	global_load_lds_dwordx4 v140, s[10:11]
	s_add_i32 m0, s14, 0x16000
	s_add_u32 s30, s73, s2
	s_addc_u32 s31, s74, s3
	s_add_i32 s15, s14, 0x2000
	v_lshl_add_u32 v142, v2, 11, v0
	global_load_lds_dwordx4 v136, s[10:11]
	s_mov_b32 m0, s14
	s_add_u32 s26, s30, 0x40000
	global_load_lds_dwordx4 v142, s[30:31]
	s_mov_b32 m0, s15
	s_addc_u32 s27, s31, 0
	s_add_i32 s10, s14, 0x4000
	global_load_lds_dwordx4 v138, s[30:31]
	s_mov_b32 m0, s10
	s_add_i32 s11, s14, 0x6000
	global_load_lds_dwordx4 v142, s[26:27]
	s_mov_b32 m0, s11
	s_cmp_eq_u32 s18, 1
	global_load_lds_dwordx4 v138, s[26:27]
	v_mov_b32_e32 v141, v191
	v_mov_b32_e32 v137, v191
	v_mov_b32_e32 v143, v191
	v_mov_b32_e32 v139, v191
	s_cselect_b64 s[2:3], -1, 0
	v_lshl_add_u64 v[4:5], s[34:35], 0, v[140:141]
	v_lshl_add_u64 v[2:3], s[34:35], 0, v[136:137]
	v_lshl_add_u64 v[0:1], s[30:31], 0, v[142:143]
	v_writelane_b32 v252, s2, 28
	s_cmp_lg_u32 s18, 1
	v_lshl_add_u64 v[6:7], s[30:31], 0, v[138:139]
	v_writelane_b32 v252, s3, 29
	s_cbranch_scc1 .LBB0_256
	s_barrier

.LBB0_531:
	s_or_b64 exec, exec, s[20:21]
	s_waitcnt lgkmcnt(0)
	s_barrier
	s_xor_b64 s[2:3], s[14:15], -1
	v_writelane_b32 v252, s2, 28
	s_nop 0
	s_nop 0
	v_writelane_b32 v252, s3, 29
	v_readlane_b32 s2, v253, 40
	v_readlane_b32 s3, v253, 41
	s_andn2_b64 vcc, exec, s[2:3]
	s_nop 0
	v_cndmask_b32_e64 v0, 0, 1, s[2:3]
	v_cmp_ne_u32_e64 s[38:39], 1, v0
	s_nop 0
	s_load_dwordx2 s[10:11], s[0:1], 0x60
	s_waitcnt lgkmcnt(0)
	s_load_dwordx2 s[34:35], s[0:1], 0x68
	s_waitcnt lgkmcnt(0)
	s_cbranch_vccnz .LBB0_543
	s_add_u32 s22, s34, 0x7000000
	s_addc_u32 s23, s35, 0
	s_add_u32 s10, s34, 0x1600000
	s_addc_u32 s11, s35, 0
	s_add_u32 s24, s34, 0x1800000
	s_addc_u32 s25, s35, 0
	s_add_u32 s26, s34, 0x6000000
	s_addc_u32 s27, s35, 0
	s_lshl_b32 s80, s16, 6
	s_lshl_b64 s[12:13], s[80:81], 2
	s_getpc_b64 s[14:15]
	s_add_u32 s14, s14, g_ctl@rel32@lo+14340
	s_addc_u32 s15, s15, g_ctl@rel32@hi+14348
	s_add_u32 s28, s14, s12
	s_addc_u32 s29, s15, s13
	v_readlane_b32 s2, v252, 5
	s_add_u32 s30, s34, s2
	v_readlane_b32 s2, v252, 6
	s_addc_u32 s31, s35, s2
	v_readlane_b32 s2, v252, 11
	s_add_u32 s34, s34, s2
	v_readlane_b32 s2, v252, 12
	s_addc_u32 s35, s35, s2
	v_readlane_b32 s2, v252, 9
	v_readlane_b32 s3, v252, 10
	v_readlane_b32 s12, v252, 4
	v_readlane_b32 s13, v252, 2
	v_readlane_b32 s3, v252, 3
	s_mov_b32 s14, s2
	s_branch .LBB0_534

.LBB0_543:
	s_and_b64 vcc, exec, s[38:39]
	s_nop 0
	s_nop 0
	s_load_dwordx2 s[34:35], s[0:1], 32
	s_waitcnt lgkmcnt(0)
	s_load_dwordx2 s[28:29], s[0:1], 40
	s_waitcnt lgkmcnt(0)
	s_load_dwordx2 s[30:31], s[0:1], 48
	s_waitcnt lgkmcnt(0)
	s_load_dwordx2 s[22:23], s[0:1], 56
	s_waitcnt lgkmcnt(0)
	s_nop 0
	s_nop 0
	s_nop 0
	s_nop 0
	s_nop 0
	s_load_dwordx2 s[10:11], s[0:1], 0x60
	s_waitcnt lgkmcnt(0)
	s_load_dwordx2 s[26:27], s[0:1], 0x68
	s_waitcnt lgkmcnt(0)
	s_cbranch_vccnz .LBB0_554
	v_readlane_b32 s100, v252, 9
	s_nop 3
	s_lshr_b32 s101, s100, 3
	s_and_b32 s100, s100, 7
	s_lshr_b32 s2, s101, 3
	s_and_b32 s3, s101, 7
	s_lshl_b32 s2, s2, 12
	s_lshl_b32 s20, s100, 9
	s_add_i32 s2, s2, s20
	s_mul_i32 s20, s2, 0x1e00
	s_lshl_b32 s3, s3, 7
	s_add_u32 s20, s20, s3
	s_add_u32 s20, s20, 0x7001200
	s_add_u32 s2, s26, s20
	s_addc_u32 s3, s27, 0
	v_lshrrev_b32_e32 v32, 3, v184
	v_mul_u32_u24_e32 v32, 0x1e00, v32
	v_and_b32_e32 v33, 7, v184
	v_lshl_add_u32 v32, v33, 4, v32
	global_load_dwordx4 v[36:39], v32, s[2:3]
	v_add_u32_e32 v33, 0x78000, v32
	global_load_dwordx4 v[40:43], v33, s[2:3]
	v_add_u32_e32 v33, 0xf0000, v32
	global_load_dwordx4 v[44:47], v33, s[2:3]
	v_add_u32_e32 v33, 0x168000, v32
	global_load_dwordx4 v[48:51], v33, s[2:3]
	v_add_u32_e32 v33, 0x1e0000, v32
	global_load_dwordx4 v[52:55], v33, s[2:3]
	v_add_u32_e32 v33, 0x258000, v32
	global_load_dwordx4 v[56:59], v33, s[2:3]
	v_add_u32_e32 v33, 0x2d0000, v32
	global_load_dwordx4 v[60:63], v33, s[2:3]
	v_add_u32_e32 v33, 0x348000, v32
	global_load_dwordx4 v[64:67], v33, s[2:3]
	v_mov_b32_e32 v70, 0
	s_waitcnt vmcnt(7)
	v_lshlrev_b32_e32 v72, 16, v36
	v_and_b32_e32 v73, 0xffff0000, v36
	v_mul_f32_e32 v71, v72, v72
	v_fmac_f32_e32 v71, v73, v73
	v_lshlrev_b32_e32 v72, 16, v37
	v_and_b32_e32 v73, 0xffff0000, v37
	v_fmac_f32_e32 v71, v72, v72
	v_fmac_f32_e32 v71, v73, v73
	v_lshlrev_b32_e32 v72, 16, v38
	v_and_b32_e32 v73, 0xffff0000, v38
	v_fmac_f32_e32 v71, v72, v72
	v_fmac_f32_e32 v71, v73, v73
	v_lshlrev_b32_e32 v72, 16, v39
	v_and_b32_e32 v73, 0xffff0000, v39
	v_fmac_f32_e32 v71, v72, v72
	v_fmac_f32_e32 v71, v73, v73
	v_max_f32_e32 v70, v70, v71
	s_waitcnt vmcnt(6)
	v_lshlrev_b32_e32 v72, 16, v40
	v_and_b32_e32 v73, 0xffff0000, v40
	v_mul_f32_e32 v71, v72, v72
	v_fmac_f32_e32 v71, v73, v73
	v_lshlrev_b32_e32 v72, 16, v41
	v_and_b32_e32 v73, 0xffff0000, v41
	v_fmac_f32_e32 v71, v72, v72
	v_fmac_f32_e32 v71, v73, v73
	v_lshlrev_b32_e32 v72, 16, v42
	v_and_b32_e32 v73, 0xffff0000, v42
	v_fmac_f32_e32 v71, v72, v72
	v_fmac_f32_e32 v71, v73, v73
	v_lshlrev_b32_e32 v72, 16, v43
	v_and_b32_e32 v73, 0xffff0000, v43
	v_fmac_f32_e32 v71, v72, v72
	v_fmac_f32_e32 v71, v73, v73
	v_max_f32_e32 v70, v70, v71
	s_waitcnt vmcnt(5)
	v_lshlrev_b32_e32 v72, 16, v44
	v_and_b32_e32 v73, 0xffff0000, v44
	v_mul_f32_e32 v71, v72, v72
	v_fmac_f32_e32 v71, v73, v73
	v_lshlrev_b32_e32 v72, 16, v45
	v_and_b32_e32 v73, 0xffff0000, v45
	v_fmac_f32_e32 v71, v72, v72
	v_fmac_f32_e32 v71, v73, v73
	v_lshlrev_b32_e32 v72, 16, v46
	v_and_b32_e32 v73, 0xffff0000, v46
	v_fmac_f32_e32 v71, v72, v72
	v_fmac_f32_e32 v71, v73, v73
	v_lshlrev_b32_e32 v72, 16, v47
	v_and_b32_e32 v73, 0xffff0000, v47
	v_fmac_f32_e32 v71, v72, v72
	v_fmac_f32_e32 v71, v73, v73
	v_max_f32_e32 v70, v70, v71
	s_waitcnt vmcnt(4)
	v_lshlrev_b32_e32 v72, 16, v48
	v_and_b32_e32 v73, 0xffff0000, v48
	v_mul_f32_e32 v71, v72, v72
	v_fmac_f32_e32 v71, v73, v73
	v_lshlrev_b32_e32 v72, 16, v49
	v_and_b32_e32 v73, 0xffff0000, v49
	v_fmac_f32_e32 v71, v72, v72
	v_fmac_f32_e32 v71, v73, v73
	v_lshlrev_b32_e32 v72, 16, v50
	v_and_b32_e32 v73, 0xffff0000, v50
	v_fmac_f32_e32 v71, v72, v72
	v_fmac_f32_e32 v71, v73, v73
	v_lshlrev_b32_e32 v72, 16, v51
	v_and_b32_e32 v73, 0xffff0000, v51
	v_fmac_f32_e32 v71, v72, v72
	v_fmac_f32_e32 v71, v73, v73
	v_max_f32_e32 v70, v70, v71
	s_waitcnt vmcnt(3)
	v_lshlrev_b32_e32 v72, 16, v52
	v_and_b32_e32 v73, 0xffff0000, v52
	v_mul_f32_e32 v71, v72, v72
	v_fmac_f32_e32 v71, v73, v73
	v_lshlrev_b32_e32 v72, 16, v53
	v_and_b32_e32 v73, 0xffff0000, v53
	v_fmac_f32_e32 v71, v72, v72
	v_fmac_f32_e32 v71, v73, v73
	v_lshlrev_b32_e32 v72, 16, v54
	v_and_b32_e32 v73, 0xffff0000, v54
	v_fmac_f32_e32 v71, v72, v72
	v_fmac_f32_e32 v71, v73, v73
	v_lshlrev_b32_e32 v72, 16, v55
	v_and_b32_e32 v73, 0xffff0000, v55
	v_fmac_f32_e32 v71, v72, v72
	v_fmac_f32_e32 v71, v73, v73
	v_max_f32_e32 v70, v70, v71
	s_waitcnt vmcnt(2)
	v_lshlrev_b32_e32 v72, 16, v56
	v_and_b32_e32 v73, 0xffff0000, v56
	v_mul_f32_e32 v71, v72, v72
	v_fmac_f32_e32 v71, v73, v73
	v_lshlrev_b32_e32 v72, 16, v57
	v_and_b32_e32 v73, 0xffff0000, v57
	v_fmac_f32_e32 v71, v72, v72
	v_fmac_f32_e32 v71, v73, v73
	v_lshlrev_b32_e32 v72, 16, v58
	v_and_b32_e32 v73, 0xffff0000, v58
	v_fmac_f32_e32 v71, v72, v72
	v_fmac_f32_e32 v71, v73, v73
	v_lshlrev_b32_e32 v72, 16, v59
	v_and_b32_e32 v73, 0xffff0000, v59
	v_fmac_f32_e32 v71, v72, v72
	v_fmac_f32_e32 v71, v73, v73
	v_max_f32_e32 v70, v70, v71
	s_waitcnt vmcnt(1)
	v_lshlrev_b32_e32 v72, 16, v60
	v_and_b32_e32 v73, 0xffff0000, v60
	v_mul_f32_e32 v71, v72, v72
	v_fmac_f32_e32 v71, v73, v73
	v_lshlrev_b32_e32 v72, 16, v61
	v_and_b32_e32 v73, 0xffff0000, v61
	v_fmac_f32_e32 v71, v72, v72
	v_fmac_f32_e32 v71, v73, v73
	v_lshlrev_b32_e32 v72, 16, v62
	v_and_b32_e32 v73, 0xffff0000, v62
	v_fmac_f32_e32 v71, v72, v72
	v_fmac_f32_e32 v71, v73, v73
	v_lshlrev_b32_e32 v72, 16, v63
	v_and_b32_e32 v73, 0xffff0000, v63
	v_fmac_f32_e32 v71, v72, v72
	v_fmac_f32_e32 v71, v73, v73
	v_max_f32_e32 v70, v70, v71
	s_waitcnt vmcnt(0)
	v_lshlrev_b32_e32 v72, 16, v64
	v_and_b32_e32 v73, 0xffff0000, v64
	v_mul_f32_e32 v71, v72, v72
	v_fmac_f32_e32 v71, v73, v73
	v_lshlrev_b32_e32 v72, 16, v65
	v_and_b32_e32 v73, 0xffff0000, v65
	v_fmac_f32_e32 v71, v72, v72
	v_fmac_f32_e32 v71, v73, v73
	v_lshlrev_b32_e32 v72, 16, v66
	v_and_b32_e32 v73, 0xffff0000, v66
	v_fmac_f32_e32 v71, v72, v72
	v_fmac_f32_e32 v71, v73, v73
	v_lshlrev_b32_e32 v72, 16, v67
	v_and_b32_e32 v73, 0xffff0000, v67
	v_fmac_f32_e32 v71, v72, v72
	v_fmac_f32_e32 v71, v73, v73
	v_max_f32_e32 v70, v70, v71
	v_and_b32_e32 v74, 63, v184
	v_lshlrev_b32_e32 v74, 2, v74
	v_xor_b32_e32 v75, 32, v74
	ds_bpermute_b32 v72, v75, v70
	s_waitcnt lgkmcnt(0)
	v_max_f32_e32 v70, v70, v72
	v_xor_b32_e32 v75, 64, v74
	ds_bpermute_b32 v72, v75, v70
	s_waitcnt lgkmcnt(0)
	v_max_f32_e32 v70, v70, v72
	v_xor_b32_e32 v75, 128, v74
	ds_bpermute_b32 v72, v75, v70
	s_waitcnt lgkmcnt(0)
	v_max_f32_e32 v70, v70, v72
	s_lshl_b32 s2, s101, 6
	s_lshl_b32 s3, s16, 11
	s_add_i32 s2, s2, s3
	s_getpc_b64 s[100:101]
	s_add_u32 s100, s100, g_ctl@rel32@lo+51204
	s_addc_u32 s101, s101, g_ctl@rel32@hi+51212
	s_add_u32 s100, s100, s2
	s_addc_u32 s101, s101, 0
	s_mov_b64 exec, 0xff
	global_atomic_umax v72, v74, v70, s[100:101] sc0
	s_waitcnt vmcnt(0)
	s_mov_b64 exec, 1
	global_atomic_add v191, v193, s[100:101] offset:32
	s_mov_b64 exec, -1
	s_add_u32 s24, s26, 0x4000000
	s_addc_u32 s25, s27, 0
	v_readlane_b32 s2, v252, 24
	s_add_u32 s26, s26, 0x7000000
	v_readlane_b32 s3, v252, 25
	s_addc_u32 s27, s27, 0
	s_lshl_b64 s[10:11], s[2:3], 2
	s_add_u32 s18, s34, s10
	s_addc_u32 s19, s35, s11
	s_add_u32 s28, s28, s10
	s_addc_u32 s29, s29, s11
	s_lshl_b32 s10, s16, 2
	s_add_u32 s30, s30, 16
	v_readlane_b32 s2, v252, 9
	s_addc_u32 s31, s31, 0
	s_lshl_b32 s11, s16, 9
	s_mov_b32 s12, s2
	s_mov_b32 s13, s2
	v_readlane_b32 s3, v252, 10
	s_branch .LBB0_546

.LBB0_554:
	v_readlane_b32 s2, v253, 42
	v_readlane_b32 s3, v253, 43
	s_andn2_b64 vcc, exec, s[2:3]
	s_nop 0
	s_nop 0
	s_nop 0
	s_nop 0
	s_nop 0
	s_nop 0
	s_nop 0
	s_nop 0
	s_nop 0
	s_load_dwordx2 s[10:11], s[0:1], 0x60
	s_waitcnt lgkmcnt(0)
	s_load_dwordx2 s[18:19], s[0:1], 0x68
	s_waitcnt lgkmcnt(0)
	s_cbranch_vccnz .LBB0_593
	s_add_u32 s22, s18, 0x7000000
	s_addc_u32 s23, s19, 0
	s_add_u32 s10, s18, 0x1500000
	s_addc_u32 s11, s19, 0
	s_add_u32 s12, s18, 0x70f1200
	v_readlane_b32 s2, v252, 9
	s_addc_u32 s13, s19, 0
	s_mov_b32 s14, s2
	v_readlane_b32 s3, v252, 10
	s_branch .LBB0_557

.LBB0_593:
	v_readlane_b32 s2, v253, 44
	v_readlane_b32 s3, v253, 45
	s_andn2_b64 vcc, exec, s[2:3]
	s_mov_b32 s4, 0x10000
	s_mov_b32 s9, 0x14000
	s_mov_b32 s26, 0xc000
	s_mov_b32 s27, 0x20000
	s_mov_b32 s28, 0x24000
	s_mov_b32 s29, 0x28000
	s_mov_b32 s30, 0x2c000
	s_mov_b32 s31, 0x30000
	s_mov_b32 s34, 0x34000
	s_load_dwordx2 s[10:11], s[0:1], 0x60
	s_waitcnt lgkmcnt(0)
	s_load_dwordx2 s[18:19], s[0:1], 0x68
	s_waitcnt lgkmcnt(0)
	s_mov_b32 s35, 0x38000
	s_mov_b32 s36, 0x3c000
	s_add_u32 s10, s18, 0x1600000
	s_addc_u32 s11, s19, 0
	s_add_u32 s12, s18, 0x1800000
	s_addc_u32 s13, s19, 0
	s_add_u32 s14, s18, 0xe800000
	s_addc_u32 s15, s19, 0
	s_lshl_b32 s80, s16, 6
	s_lshl_b64 s[18:19], s[80:81], 2
	s_getpc_b64 s[20:21]
	s_add_u32 s20, s20, g_ctl@rel32@lo+14340
	s_addc_u32 s21, s21, g_ctl@rel32@hi+14348
	s_add_u32 s18, s20, s18
	v_readlane_b32 s2, v252, 9
	s_addc_u32 s19, s21, s19
	s_mov_b32 s20, s2
	v_readlane_b32 s3, v252, 10
	s_branch .LBB0_597

.LBB0_654:
	s_or_b64 exec, exec, s[18:19]
	s_waitcnt lgkmcnt(0)
	s_barrier
	s_and_b64 vcc, exec, s[38:39]
	v_readlane_b32 s3, v252, 16
	s_nop 0
	s_nop 0
	s_nop 0
	s_nop 0
	s_nop 0
	s_nop 0
	s_load_dwordx2 s[24:25], s[0:1], 0x48
	s_waitcnt lgkmcnt(0)
	s_nop 0
	s_nop 0
	s_nop 0
	s_load_dwordx2 s[10:11], s[0:1], 0x60
	s_waitcnt lgkmcnt(0)
	s_load_dwordx2 s[26:27], s[0:1], 0x68
	s_waitcnt lgkmcnt(0)
	s_cbranch_vccnz .LBB0_687
	s_add_u32 s10, s26, 0x4000000
	s_addc_u32 s11, s27, 0
	s_add_u32 s18, s26, 0x7000000
	s_addc_u32 s19, s27, 0
	s_add_u32 s22, s26, 0x6000000
	s_addc_u32 s23, s27, 0
	s_add_u32 s12, s26, 0xe800000
	s_addc_u32 s13, s27, 0
	s_lshl_b32 s80, s16, 6
	s_lshl_b64 s[14:15], s[80:81], 2
	s_add_u32 s24, s24, s14
	s_addc_u32 s25, s25, s15
	v_readlane_b32 s26, v252, 9
	v_readlane_b32 s27, v252, 10
	s_branch .LBB0_657

.LBB0_735:
	s_or_b64 exec, exec, s[18:19]
	s_waitcnt lgkmcnt(0)
	s_barrier
	s_load_dwordx2 s[26:27], s[0:1], 0
	s_waitcnt lgkmcnt(0)
	s_nop 0
	s_nop 0
	s_nop 0
	s_nop 0
	s_nop 0
	s_nop 0
	s_nop 0
	s_nop 0
	s_nop 0
	s_load_dwordx2 s[10:11], s[0:1], 0x50
	s_waitcnt lgkmcnt(0)
	s_load_dwordx2 s[18:19], s[0:1], 0x58
	s_waitcnt lgkmcnt(0)
	s_load_dwordx2 s[22:23], s[0:1], 0x60
	s_waitcnt lgkmcnt(0)
	s_load_dwordx2 s[24:25], s[0:1], 0x68
	s_waitcnt lgkmcnt(0)
	s_add_u32 s52, s24, 0x4000000
	s_addc_u32 s53, s25, 0
	s_lshl_b64 s[10:11], s[16:17], 21
	s_add_u32 s2, s24, s10
	s_addc_u32 s3, s25, s11
	s_add_u32 s54, s2, 0x1000000
	s_addc_u32 s55, s3, 0
	v_readlane_b32 s2, v253, 46
	v_readlane_b32 s10, v252, 20
	v_readlane_b32 s3, v253, 47
	v_readlane_b32 s11, v252, 21
	s_and_b64 s[10:11], s[2:3], s[10:11]
	v_readlane_b32 s2, v253, 50
	v_readlane_b32 s3, v253, 51
	s_xor_b64 s[14:15], s[10:11], -1
	s_mov_b64 s[16:17], -1
	v_cndmask_b32_e64 v0, 0, 1, s[2:3]
	s_and_b64 vcc, exec, s[14:15]
	v_cmp_ne_u32_e64 s[38:39], 1, v0
	s_cbranch_vccz .LBB0_773
	v_mov_b32_e32 v14, v184
	s_and_b64 vcc, exec, s[38:39]
	v_readfirstlane_b32 s20, v14
	s_cbranch_vccnz .LBB0_772
	v_lshlrev_b32_e32 v0, 4, v14
	v_add_u32_e32 v1, 0x2000, v0
	v_ashrrev_i32_e32 v2, 31, v1
	v_lshrrev_b32_e32 v2, 22, v2
	v_add_u32_e32 v2, v1, v2
	v_ashrrev_i32_e32 v8, 10, v2
	v_mul_i32_i24_e32 v2, 0x400, v8
	v_sub_u32_e32 v1, v1, v2
	v_lshrrev_b32_e32 v2, 4, v1
	v_bitop3_b32 v1, v2, v1, 32 bitop3:0x6c
	v_ashrrev_i32_e32 v2, 31, v1
	v_lshrrev_b32_e32 v2, 26, v2
	v_add_u32_e32 v2, v1, v2
	v_lshlrev_b32_e32 v3, 3, v8
	v_ashrrev_i32_e32 v9, 6, v2
	v_and_b32_e32 v3, -16, v3
	v_add_u32_e32 v3, v9, v3
	v_and_b32_e32 v4, 3, v9
	s_mov_b32 s2, 0x1fffe0
	v_lshrrev_b32_e32 v5, 2, v3
	v_lshlrev_b32_e32 v6, 1, v3
	v_and_b32_e32 v2, 0xc0, v2
	v_and_or_b32 v4, v3, s2, v4
	v_and_b32_e32 v5, 4, v5
	v_and_b32_e32 v6, 24, v6
	v_sub_u32_e32 v1, v1, v2
	v_or3_b32 v4, v4, v5, v6
	v_lshlrev_b32_e32 v5, 5, v8
	v_ashrrev_i16_sdwa v1, v193, sext(v1) dst_sel:DWORD dst_unused:UNUSED_PAD src0_sel:DWORD src1_sel:BYTE_0
	v_and_b32_e32 v5, 32, v5
	v_bfe_i32 v10, v1, 0, 16
	v_add_lshl_u32 v1, v5, v10, 1
	v_lshl_add_u32 v202, v4, 11, v1
	v_lshl_add_u32 v204, v3, 11, v1
	v_bfe_i32 v1, v14, 27, 1
	v_lshrrev_b32_e32 v1, 22, v1
	v_add_u32_e32 v1, v0, v1
	v_and_b32_e32 v1, 0xfffffc00, v1
	v_sub_u32_e32 v0, v0, v1
	v_lshrrev_b32_e32 v1, 4, v0
	v_ashrrev_i32_e32 v2, 31, v14
	v_bitop3_b32 v0, v1, v0, 32 bitop3:0x6c
	v_lshrrev_b32_e32 v2, 26, v2
	v_ashrrev_i32_e32 v1, 31, v0
	v_add_u32_e32 v2, v14, v2
	v_lshrrev_b32_e32 v1, 26, v1
	v_ashrrev_i32_e32 v12, 6, v2
	v_add_u32_e32 v1, v0, v1
	v_lshlrev_b32_e32 v2, 3, v12
	v_ashrrev_i32_e32 v11, 6, v1
	v_and_b32_e32 v2, -16, v2
	v_add_u32_e32 v2, v11, v2
	v_and_b32_e32 v3, 3, v11
	v_lshrrev_b32_e32 v4, 2, v2
	v_lshlrev_b32_e32 v5, 1, v2
	v_and_b32_e32 v1, 0xc0, v1
	s_ashr_i32 s21, s20, 6
	v_and_or_b32 v3, v2, s2, v3
	v_and_b32_e32 v4, 4, v4
	v_and_b32_e32 v5, 24, v5
	v_sub_u32_e32 v0, v0, v1
	s_ashr_i32 s28, s20, 8
	s_lshl_b32 s56, s21, 10
	v_or3_b32 v3, v3, v4, v5
	v_lshlrev_b32_e32 v4, 5, v12
	v_ashrrev_i16_sdwa v0, v193, sext(v0) dst_sel:DWORD dst_unused:UNUSED_PAD src0_sel:DWORD src1_sel:BYTE_0
	v_readlane_b32 s2, v252, 0
	v_and_b32_e32 v4, 32, v4
	v_bfe_i32 v13, v0, 0, 16
	v_readlane_b32 s3, v252, 1
	s_add_u32 s48, s54, s2
	v_add_lshl_u32 v0, v4, v13, 1
	s_addc_u32 s49, s55, s3
	s_add_i32 s57, s56, 0
	v_lshl_add_u32 v190, v3, 11, v0
	s_add_i32 m0, s57, 0x10000
	v_readlane_b32 s2, v253, 62
	global_load_lds_dwordx4 v190, s[48:49]
	s_add_i32 m0, s57, 0x12000
	s_add_u32 s10, s48, 0x40000
	global_load_lds_dwordx4 v202, s[48:49]
	s_addc_u32 s11, s49, 0
	s_add_i32 m0, s57, 0x14000
	v_readlane_b32 s3, v253, 63
	global_load_lds_dwordx4 v190, s[10:11]
	s_add_i32 m0, s57, 0x16000
	s_add_u32 s36, s52, s2
	s_addc_u32 s37, s53, s3
	s_add_i32 s68, s57, 0x2000
	v_lshl_add_u32 v206, v2, 11, v0
	global_load_lds_dwordx4 v202, s[10:11]
	s_mov_b32 m0, s57
	s_add_u32 s10, s36, 0x40000
	global_load_lds_dwordx4 v206, s[36:37]
	s_mov_b32 m0, s68
	s_addc_u32 s11, s37, 0
	s_add_i32 s69, s57, 0x4000
	global_load_lds_dwordx4 v204, s[36:37]
	s_mov_b32 m0, s69
	s_add_i32 s73, s57, 0x6000
	global_load_lds_dwordx4 v206, s[10:11]
	s_mov_b32 m0, s73
	v_mov_b32_e32 v203, v191
	global_load_lds_dwordx4 v204, s[10:11]
	v_mov_b32_e32 v207, v191
	v_mov_b32_e32 v205, v191
	s_cmp_eq_u32 s28, 1
	v_lshl_add_u64 v[6:7], s[48:49], 0, v[190:191]
	v_lshl_add_u64 v[4:5], s[48:49], 0, v[202:203]
	v_lshl_add_u64 v[0:1], s[36:37], 0, v[206:207]
	s_cselect_b64 s[16:17], -1, 0
	s_cmp_lg_u32 s28, 1
	v_lshl_add_u64 v[2:3], s[36:37], 0, v[204:205]
	s_cbranch_scc1 .LBB0_739
	s_barrier

.LBB0_870:
	v_readlane_b32 s2, v253, 48
	v_readlane_b32 s3, v253, 49
	s_and_b64 vcc, exec, s[2:3]
	s_cbranch_vccz .LBB0_875
	v_mov_b32_e32 v0, v184
	v_readlane_b32 s12, v253, 2
	v_readlane_b32 s13, v253, 3
	s_nop 0
	s_nop 0
	s_nop 0
	s_nop 0
	s_nop 0
	s_nop 0
	s_nop 0
	s_load_dwordx2 s[6:7], s[0:1], 0x58
	s_waitcnt lgkmcnt(0)
	s_load_dwordx2 s[4:5], s[0:1], 0x60
	s_waitcnt lgkmcnt(0)
	s_nop 0
	s_load_dwordx2 s[2:3], s[0:1], 0x68
	s_waitcnt lgkmcnt(0)
	s_movk_i32 s0, 0x4000
	v_ashrrev_i32_e32 v2, 6, v0
	v_add_u32_e32 v6, s12, v2
	v_cmp_gt_i32_e32 vcc, s0, v6
	s_and_saveexec_b64 s[0:1], vcc
	v_readlane_b32 s10, v253, 4
	v_readlane_b32 s11, v253, 5
	s_cbranch_execz .LBB0_874
	v_ashrrev_i32_e32 v3, 31, v2
	s_ashr_i32 s13, s12, 31
	v_lshlrev_b32_e32 v0, 4, v0
	v_lshl_add_u64 v[8:9], v[2:3], 0, s[12:13]
	v_and_b32_e32 v4, 0x3f0, v0
	v_lshl_add_u64 v[2:3], v[8:9], 2, s[2:3]
	v_lshlrev_b64 v[8:9], 12, v[8:9]
	v_mov_b32_e32 v5, 0
	v_or_b32_e32 v8, v8, v4
	s_waitcnt lgkmcnt(0)
	v_lshl_add_u64 v[0:1], s[6:7], 0, v[4:5]
	s_mov_b64 s[2:3], 0x1420000
	s_ashr_i32 s11, s10, 31
	v_lshl_add_u64 v[4:5], s[4:5], 0, v[8:9]
	s_mov_b64 s[4:5], 0xc00
	v_lshl_add_u64 v[2:3], v[2:3], 0, s[2:3]
	s_lshl_b64 s[2:3], s[10:11], 2
	v_lshl_add_u64 v[4:5], v[4:5], 0, s[4:5]
	s_lshl_b64 s[4:5], s[10:11], 12
	s_mov_b64 s[6:7], 0
	v_mov_b32_e32 v7, 0x358637bd
	s_mov_b32 s8, 0x800000
	s_movk_i32 s9, 0x3fff
